# fast f32 rcp division in all GEMM epilogues + attention; RES epilogue (latent tiles) pipelined: 12 base loads in flight with counted vmcnt instead of load/vmcnt(0)/fma/store per block
# baseline (speedup 1.0000x reference)
.LBB0_906:
	s_andn2_b64 vcc, exec, s[8:9]
	s_cbranch_vccnz .LBB0_1036
	s_cmp_lt_i32 s66, 64
	s_cselect_b64 s[2:3], -1, 0
	s_cmp_gt_i32 s66, 63
	s_movk_i32 s4, 0x68
	s_cselect_b32 s4, 0x70, s4
	s_movk_i32 s5, 0x48
	s_movk_i32 s7, 0x58
	v_readlane_b32 s8, v253, 34
	s_cselect_b32 s5, 0x50, s5
	s_cselect_b32 s6, 0xffffc000, 0
	s_cselect_b32 s7, 0x60, s7
	s_add_i32 s4, s8, s4
	v_mov_b32_e32 v0, s4
	ds_read_b64 v[130:131], v0
	s_add_i32 s4, s8, s5
	v_ashrrev_i32_e32 v163, 31, v162
	v_mov_b32_e32 v0, s4
	s_add_i32 s4, s8, s7
	v_mov_b32_e32 v132, s4
	s_waitcnt lgkmcnt(0)
	v_lshl_add_u64 v[130:131], v[162:163], 2, v[130:131]
	ds_read_b64 v[166:167], v0
	ds_read_b64 v[164:165], v132
	global_load_dwordx4 v[142:145], v[130:131], off
	global_load_dwordx4 v[138:141], v[130:131], off offset:64
	global_load_dwordx4 v[134:137], v[130:131], off offset:512
	s_nop 0
	global_load_dwordx4 v[130:133], v[130:131], off offset:576
	v_add_u32_e32 v168, s6, v160
	v_ashrrev_i32_e32 v169, 31, v168
	v_lshlrev_b64 v[146:147], 10, v[168:169]
	v_lshl_add_u64 v[170:171], v[146:147], 0, v[162:163]
	v_lshlrev_b64 v[146:147], 2, v[170:171]
	s_waitcnt lgkmcnt(0)
	v_lshl_add_u64 v[172:173], v[166:167], 0, v[146:147]
	v_lshl_add_u64 v[174:175], v[164:165], 0, v[146:147]
	s_and_b64 vcc, exec, s[2:3]
	s_cbranch_vccnz .Lres_fast
	s_mov_b64 s[4:5], -1
	s_and_b64 vcc, exec, s[2:3]
	s_cbranch_vccz .LBB0_909
	global_load_dwordx4 v[146:149], v[172:173], off
	s_mov_b64 s[4:5], 0
	s_waitcnt vmcnt(0)
	v_pk_fma_f32 v[148:149], v[128:129], v[144:145], v[148:149]
	v_pk_fma_f32 v[146:147], v[126:127], v[142:143], v[146:147]
	global_store_dwordx4 v[174:175], v[146:149], off

.Lres_fast:
	s_mov_b64 s[4:5], 0x10000
	s_mov_b64 s[6:7], 0x50000
	global_load_dwordx4 v[206:209], v[172:173], off
	global_load_dwordx4 v[210:213], v[172:173], off offset:64
	global_load_dwordx4 v[214:217], v[172:173], off offset:512
	global_load_dwordx4 v[218:221], v[172:173], off offset:576
	v_lshl_add_u64 v[172:173], v[172:173], 0, s[4:5]
	global_load_dwordx4 v[222:225], v[172:173], off
	global_load_dwordx4 v[226:229], v[172:173], off offset:64
	global_load_dwordx4 v[236:239], v[172:173], off offset:512
	global_load_dwordx4 v[240:243], v[172:173], off offset:576
	v_lshl_add_u64 v[172:173], v[172:173], 0, s[4:5]
	global_load_dwordx4 v[244:247], v[172:173], off
	global_load_dwordx4 v[146:149], v[172:173], off offset:64
	global_load_dwordx4 v[168:171], v[172:173], off offset:512
	global_load_dwordx4 v[164:167], v[172:173], off offset:576
	v_lshl_add_u64 v[172:173], v[172:173], 0, s[4:5]
	s_waitcnt vmcnt(8)
	v_pk_fma_f32 v[206:207], v[126:127], v[142:143], v[206:207]
	v_pk_fma_f32 v[208:209], v[128:129], v[144:145], v[208:209]
	v_pk_fma_f32 v[210:211], v[118:119], v[138:139], v[210:211]
	v_pk_fma_f32 v[212:213], v[120:121], v[140:141], v[212:213]
	v_pk_fma_f32 v[214:215], v[122:123], v[134:135], v[214:215]
	v_pk_fma_f32 v[216:217], v[124:125], v[136:137], v[216:217]
	v_pk_fma_f32 v[218:219], v[114:115], v[130:131], v[218:219]
	v_pk_fma_f32 v[220:221], v[116:117], v[132:133], v[220:221]
	global_store_dwordx4 v[174:175], v[206:209], off
	global_store_dwordx4 v[174:175], v[210:213], off offset:64
	global_store_dwordx4 v[174:175], v[214:217], off offset:512
	global_store_dwordx4 v[174:175], v[218:221], off offset:576
	v_lshl_add_u64 v[174:175], v[174:175], 0, s[4:5]
	global_load_dwordx4 v[206:209], v[172:173], off
	global_load_dwordx4 v[210:213], v[172:173], off offset:64
	global_load_dwordx4 v[214:217], v[172:173], off offset:512
	global_load_dwordx4 v[218:221], v[172:173], off offset:576
	v_lshl_add_u64 v[172:173], v[172:173], 0, s[6:7]
	s_waitcnt vmcnt(12)
	v_pk_fma_f32 v[222:223], v[110:111], v[142:143], v[222:223]
	v_pk_fma_f32 v[224:225], v[112:113], v[144:145], v[224:225]
	v_pk_fma_f32 v[226:227], v[102:103], v[138:139], v[226:227]
	v_pk_fma_f32 v[228:229], v[104:105], v[140:141], v[228:229]
	v_pk_fma_f32 v[236:237], v[106:107], v[134:135], v[236:237]
	v_pk_fma_f32 v[238:239], v[108:109], v[136:137], v[238:239]
	v_pk_fma_f32 v[240:241], v[98:99], v[130:131], v[240:241]
	v_pk_fma_f32 v[242:243], v[100:101], v[132:133], v[242:243]
	global_store_dwordx4 v[174:175], v[222:225], off
	global_store_dwordx4 v[174:175], v[226:229], off offset:64
	global_store_dwordx4 v[174:175], v[236:239], off offset:512
	global_store_dwordx4 v[174:175], v[240:243], off offset:576
	v_lshl_add_u64 v[174:175], v[174:175], 0, s[4:5]
	global_load_dwordx4 v[222:225], v[172:173], off
	global_load_dwordx4 v[226:229], v[172:173], off offset:64
	global_load_dwordx4 v[236:239], v[172:173], off offset:512
	global_load_dwordx4 v[240:243], v[172:173], off offset:576
	v_lshl_add_u64 v[172:173], v[172:173], 0, s[4:5]
	s_waitcnt vmcnt(16)
	v_pk_fma_f32 v[244:245], v[94:95], v[142:143], v[244:245]
	v_pk_fma_f32 v[246:247], v[96:97], v[144:145], v[246:247]
	v_pk_fma_f32 v[146:147], v[86:87], v[138:139], v[146:147]
	v_pk_fma_f32 v[148:149], v[88:89], v[140:141], v[148:149]
	v_pk_fma_f32 v[168:169], v[90:91], v[134:135], v[168:169]
	v_pk_fma_f32 v[170:171], v[92:93], v[136:137], v[170:171]
	v_pk_fma_f32 v[164:165], v[82:83], v[130:131], v[164:165]
	v_pk_fma_f32 v[166:167], v[84:85], v[132:133], v[166:167]
	global_store_dwordx4 v[174:175], v[244:247], off
	global_store_dwordx4 v[174:175], v[146:149], off offset:64
	global_store_dwordx4 v[174:175], v[168:171], off offset:512
	global_store_dwordx4 v[174:175], v[164:167], off offset:576
	v_lshl_add_u64 v[174:175], v[174:175], 0, s[4:5]
	global_load_dwordx4 v[244:247], v[172:173], off
	global_load_dwordx4 v[146:149], v[172:173], off offset:64
	global_load_dwordx4 v[168:171], v[172:173], off offset:512
	global_load_dwordx4 v[164:167], v[172:173], off offset:576
	v_lshl_add_u64 v[172:173], v[172:173], 0, s[4:5]
	s_waitcnt vmcnt(16)
	v_pk_fma_f32 v[206:207], v[78:79], v[142:143], v[206:207]
	v_pk_fma_f32 v[208:209], v[80:81], v[144:145], v[208:209]
	v_pk_fma_f32 v[210:211], v[70:71], v[138:139], v[210:211]
	v_pk_fma_f32 v[212:213], v[72:73], v[140:141], v[212:213]
	v_pk_fma_f32 v[214:215], v[74:75], v[134:135], v[214:215]
	v_pk_fma_f32 v[216:217], v[76:77], v[136:137], v[216:217]
	v_pk_fma_f32 v[218:219], v[66:67], v[130:131], v[218:219]
	v_pk_fma_f32 v[220:221], v[68:69], v[132:133], v[220:221]
	global_store_dwordx4 v[174:175], v[206:209], off
	global_store_dwordx4 v[174:175], v[210:213], off offset:64
	global_store_dwordx4 v[174:175], v[214:217], off offset:512
	global_store_dwordx4 v[174:175], v[218:221], off offset:576
	v_lshl_add_u64 v[174:175], v[174:175], 0, s[6:7]
	global_load_dwordx4 v[206:209], v[172:173], off
	global_load_dwordx4 v[210:213], v[172:173], off offset:64
	global_load_dwordx4 v[214:217], v[172:173], off offset:512
	global_load_dwordx4 v[218:221], v[172:173], off offset:576
	v_lshl_add_u64 v[172:173], v[172:173], 0, s[4:5]
	s_waitcnt vmcnt(16)
	v_pk_fma_f32 v[222:223], v[62:63], v[142:143], v[222:223]
	v_pk_fma_f32 v[224:225], v[64:65], v[144:145], v[224:225]
	v_pk_fma_f32 v[226:227], v[54:55], v[138:139], v[226:227]
	v_pk_fma_f32 v[228:229], v[56:57], v[140:141], v[228:229]
	v_pk_fma_f32 v[236:237], v[58:59], v[134:135], v[236:237]
	v_pk_fma_f32 v[238:239], v[60:61], v[136:137], v[238:239]
	v_pk_fma_f32 v[240:241], v[50:51], v[130:131], v[240:241]
	v_pk_fma_f32 v[242:243], v[52:53], v[132:133], v[242:243]
	global_store_dwordx4 v[174:175], v[222:225], off
	global_store_dwordx4 v[174:175], v[226:229], off offset:64
	global_store_dwordx4 v[174:175], v[236:239], off offset:512
	global_store_dwordx4 v[174:175], v[240:243], off offset:576
	v_lshl_add_u64 v[174:175], v[174:175], 0, s[4:5]
	global_load_dwordx4 v[222:225], v[172:173], off
	global_load_dwordx4 v[226:229], v[172:173], off offset:64
	global_load_dwordx4 v[236:239], v[172:173], off offset:512
	global_load_dwordx4 v[240:243], v[172:173], off offset:576
	s_waitcnt vmcnt(16)
	v_pk_fma_f32 v[244:245], v[46:47], v[142:143], v[244:245]
	v_pk_fma_f32 v[246:247], v[48:49], v[144:145], v[246:247]
	v_pk_fma_f32 v[146:147], v[38:39], v[138:139], v[146:147]
	v_pk_fma_f32 v[148:149], v[40:41], v[140:141], v[148:149]
	v_pk_fma_f32 v[168:169], v[42:43], v[134:135], v[168:169]
	v_pk_fma_f32 v[170:171], v[44:45], v[136:137], v[170:171]
	v_pk_fma_f32 v[164:165], v[34:35], v[130:131], v[164:165]
	v_pk_fma_f32 v[166:167], v[36:37], v[132:133], v[166:167]
	global_store_dwordx4 v[174:175], v[244:247], off
	global_store_dwordx4 v[174:175], v[146:149], off offset:64
	global_store_dwordx4 v[174:175], v[168:171], off offset:512
	global_store_dwordx4 v[174:175], v[164:167], off offset:576
	v_lshl_add_u64 v[174:175], v[174:175], 0, s[4:5]
	s_waitcnt vmcnt(12)
	v_pk_fma_f32 v[206:207], v[30:31], v[142:143], v[206:207]
	v_pk_fma_f32 v[208:209], v[32:33], v[144:145], v[208:209]
	v_pk_fma_f32 v[210:211], v[22:23], v[138:139], v[210:211]
	v_pk_fma_f32 v[212:213], v[24:25], v[140:141], v[212:213]
	v_pk_fma_f32 v[214:215], v[26:27], v[134:135], v[214:215]
	v_pk_fma_f32 v[216:217], v[28:29], v[136:137], v[216:217]
	v_pk_fma_f32 v[218:219], v[18:19], v[130:131], v[218:219]
	v_pk_fma_f32 v[220:221], v[20:21], v[132:133], v[220:221]
	global_store_dwordx4 v[174:175], v[206:209], off
	global_store_dwordx4 v[174:175], v[210:213], off offset:64
	global_store_dwordx4 v[174:175], v[214:217], off offset:512
	global_store_dwordx4 v[174:175], v[218:221], off offset:576
	v_lshl_add_u64 v[174:175], v[174:175], 0, s[4:5]
	s_waitcnt vmcnt(8)
	v_pk_fma_f32 v[222:223], v[14:15], v[142:143], v[222:223]
	v_pk_fma_f32 v[224:225], v[16:17], v[144:145], v[224:225]
	v_pk_fma_f32 v[226:227], v[6:7], v[138:139], v[226:227]
	v_pk_fma_f32 v[228:229], v[8:9], v[140:141], v[228:229]
	v_pk_fma_f32 v[236:237], v[10:11], v[134:135], v[236:237]
	v_pk_fma_f32 v[238:239], v[12:13], v[136:137], v[238:239]
	v_pk_fma_f32 v[240:241], v[2:3], v[130:131], v[240:241]
	v_pk_fma_f32 v[242:243], v[4:5], v[132:133], v[242:243]
	global_store_dwordx4 v[174:175], v[222:225], off
	global_store_dwordx4 v[174:175], v[226:229], off offset:64
	global_store_dwordx4 v[174:175], v[236:239], off offset:512
	global_store_dwordx4 v[174:175], v[240:243], off offset:576
	s_branch .LBB0_816
